# UP pass sharing with 14 helper workgroups (tiles 4..17) instead of 28
# speedup vs baseline: 1.0723x; 1.0097x over previous
; DI const bf16_t* wp(const Params& p, int l, size_t off) { return (const bf16_t*)(p.ws + OFF_WP) + (size_t)l * PW_LAYER + off; }
; template <int MT> DI void phaseB(const Params& p, int l, int t, unsigned char* lds) {
;     ...
;     EpiUp<MT> eu; eu.priv = priv; eu.d2 = d2;
;     eu.halo = (float*)(ws + OFF_UHALO) + (size_t)t * 2 * DFF2;
;     eu.pconv = t == NTILE - 1 ? p.out + O_PCONV + (size_t)l * 2 * DFF2 : nullptr;
;     eu.sconv = p.out + O_SCONV + ((size_t)l * 8 + 2 * t) * 2 * DFF2;
;     gemm64<1024, MT>(xb, DM, d2, wp(p, l, PW_UP), DFF2 / UW, lds, eu);
.LBB0_705:
	v_readlane_b32 s0, v254, 57
	s_cmp_lt_u32 s0, 4
	s_cbranch_scc1 .Lhu_done
	s_cmp_gt_u32 s0, 17
	s_cbranch_scc1 .Lhu_done
	v_writelane_b32 v180, s0, 0
	v_writelane_b32 v180, s1, 1
	v_writelane_b32 v180, s2, 2
	v_writelane_b32 v180, s3, 3
	v_writelane_b32 v180, s4, 4
	v_writelane_b32 v180, s5, 5
	v_writelane_b32 v180, s6, 6
	v_writelane_b32 v180, s7, 7
	v_writelane_b32 v180, s8, 8
	v_writelane_b32 v180, s9, 9
	v_writelane_b32 v180, s10, 10
	v_writelane_b32 v180, s11, 11
	v_writelane_b32 v180, s12, 12
	v_writelane_b32 v180, s13, 13
	v_writelane_b32 v180, s14, 14
	v_writelane_b32 v180, s15, 15
	v_writelane_b32 v180, s16, 16
	v_writelane_b32 v180, s17, 17
	v_writelane_b32 v180, s18, 18
	v_writelane_b32 v180, s19, 19
	v_writelane_b32 v180, s20, 20
	v_writelane_b32 v180, s21, 21
	v_writelane_b32 v180, s22, 22
	v_writelane_b32 v180, s23, 23
	v_writelane_b32 v180, s24, 24
	v_writelane_b32 v180, s25, 25
	v_writelane_b32 v180, s26, 26
	v_writelane_b32 v180, s27, 27
	v_writelane_b32 v180, s28, 28
	v_writelane_b32 v180, s29, 29
	v_writelane_b32 v180, s30, 30
	v_writelane_b32 v180, s31, 31
	v_writelane_b32 v180, s32, 32
	v_writelane_b32 v180, s33, 33
	v_writelane_b32 v180, s34, 34
	v_writelane_b32 v180, s35, 35
	v_writelane_b32 v180, s36, 36
	v_writelane_b32 v180, s37, 37
	v_writelane_b32 v180, s38, 38
	v_writelane_b32 v180, s39, 39
	v_writelane_b32 v180, s40, 40
	v_writelane_b32 v180, s41, 41
	v_writelane_b32 v180, s42, 42
	v_writelane_b32 v180, s43, 43
	v_writelane_b32 v180, s44, 44
	v_writelane_b32 v180, s45, 45
	v_writelane_b32 v180, s46, 46
	v_writelane_b32 v180, s47, 47
	v_writelane_b32 v180, s48, 48
	v_writelane_b32 v180, s49, 49
	v_writelane_b32 v180, s50, 50
	v_writelane_b32 v180, s51, 51
	v_writelane_b32 v180, s52, 52
	v_writelane_b32 v180, s53, 53
	v_writelane_b32 v180, s54, 54
	v_writelane_b32 v180, s55, 55
	v_writelane_b32 v180, s56, 56
	v_writelane_b32 v180, s57, 57
	v_writelane_b32 v180, s58, 58
	v_writelane_b32 v180, s59, 59
	v_writelane_b32 v180, s60, 60
	v_writelane_b32 v180, s61, 61
	v_writelane_b32 v180, s62, 62
	v_writelane_b32 v180, s63, 63
	v_writelane_b32 v181, s64, 0
	v_writelane_b32 v181, s65, 1
	v_writelane_b32 v181, s66, 2
	v_writelane_b32 v181, s67, 3
	v_writelane_b32 v181, s68, 4
	v_writelane_b32 v181, s69, 5
	v_writelane_b32 v181, s70, 6
	v_writelane_b32 v181, s71, 7
	v_writelane_b32 v181, s72, 8
	v_writelane_b32 v181, s73, 9
	v_writelane_b32 v181, s74, 10
	v_writelane_b32 v181, s75, 11
	v_writelane_b32 v181, s76, 12
	v_writelane_b32 v181, s77, 13
	v_writelane_b32 v181, s78, 14
	v_writelane_b32 v181, s79, 15
	v_writelane_b32 v181, s80, 16
	v_writelane_b32 v181, s81, 17
	v_writelane_b32 v181, s82, 18
	v_writelane_b32 v181, s83, 19
	v_writelane_b32 v181, s84, 20
	v_writelane_b32 v181, s85, 21
	v_writelane_b32 v181, s86, 22
	v_writelane_b32 v181, s87, 23
	v_writelane_b32 v181, s88, 24
	v_writelane_b32 v181, s89, 25
	v_writelane_b32 v181, s90, 26
	v_writelane_b32 v181, s91, 27
	v_writelane_b32 v181, s92, 28
	v_writelane_b32 v181, s93, 29
	v_writelane_b32 v181, s94, 30
	v_writelane_b32 v181, s95, 31
	v_writelane_b32 v181, s96, 32
	v_writelane_b32 v181, s97, 33
	v_writelane_b32 v181, s98, 34
	v_writelane_b32 v181, s99, 35
	v_writelane_b32 v181, s100, 36
	v_writelane_b32 v181, s101, 37
	v_writelane_b32 v181, vcc_lo, 38
	v_writelane_b32 v181, vcc_hi, 39
	s_getreg_b32 s70, hwreg(HW_REG_XCC_ID, 0, 4)
	s_mov_b32 s43, 0xb0000
	s_movk_i32 s44, 0x1600
	s_mov_b32 s65, 0
	v_readlane_b32 s66, v252, 10
	v_readlane_b32 s67, v252, 11
	v_readlane_b32 s68, v254, 57
	s_mov_b32 s69, 0
	s_mov_b32 s80, 0
	v_lshrrev_b32_e32 v223, 6, v176

; DI const bf16_t* wp(const Params& p, int l, size_t off) { return (const bf16_t*)(p.ws + OFF_WP) + (size_t)l * PW_LAYER + off; }
; template <int MT> DI void phaseB(const Params& p, int l, int t, unsigned char* lds) {
;     ...
;     EpiUp<MT> eu; eu.priv = priv; eu.d2 = d2;
;     eu.halo = (float*)(ws + OFF_UHALO) + (size_t)t * 2 * DFF2;
;     eu.pconv = t == NTILE - 1 ? p.out + O_PCONV + (size_t)l * 2 * DFF2 : nullptr;
;     eu.sconv = p.out + O_SCONV + ((size_t)l * 8 + 2 * t) * 2 * DFF2;
;     gemm64<1024, MT>(xb, DM, d2, wp(p, l, PW_UP), DFF2 / UW, lds, eu);
.Lhu_next:
	s_add_u32 s69, s69, 1
	s_cmp_lt_u32 s69, 4
	s_cbranch_scc1 .Lhu_target
	v_readlane_b32 s0, v180, 0
	v_readlane_b32 s1, v180, 1
	v_readlane_b32 s2, v180, 2
	v_readlane_b32 s3, v180, 3
	v_readlane_b32 s4, v180, 4
	v_readlane_b32 s5, v180, 5
	v_readlane_b32 s6, v180, 6
	v_readlane_b32 s7, v180, 7
	v_readlane_b32 s8, v180, 8
	v_readlane_b32 s9, v180, 9
	v_readlane_b32 s10, v180, 10
	v_readlane_b32 s11, v180, 11
	v_readlane_b32 s12, v180, 12
	v_readlane_b32 s13, v180, 13
	v_readlane_b32 s14, v180, 14
	v_readlane_b32 s15, v180, 15
	v_readlane_b32 s16, v180, 16
	v_readlane_b32 s17, v180, 17
	v_readlane_b32 s18, v180, 18
	v_readlane_b32 s19, v180, 19
	v_readlane_b32 s20, v180, 20
	v_readlane_b32 s21, v180, 21
	v_readlane_b32 s22, v180, 22
	v_readlane_b32 s23, v180, 23
	v_readlane_b32 s24, v180, 24
	v_readlane_b32 s25, v180, 25
	v_readlane_b32 s26, v180, 26
	v_readlane_b32 s27, v180, 27
	v_readlane_b32 s28, v180, 28
	v_readlane_b32 s29, v180, 29
	v_readlane_b32 s30, v180, 30
	v_readlane_b32 s31, v180, 31
	v_readlane_b32 s32, v180, 32
	v_readlane_b32 s33, v180, 33
	v_readlane_b32 s34, v180, 34
	v_readlane_b32 s35, v180, 35
	v_readlane_b32 s36, v180, 36
	v_readlane_b32 s37, v180, 37
	v_readlane_b32 s38, v180, 38
	v_readlane_b32 s39, v180, 39
	v_readlane_b32 s40, v180, 40
	v_readlane_b32 s41, v180, 41
	v_readlane_b32 s42, v180, 42
	v_readlane_b32 s43, v180, 43
	v_readlane_b32 s44, v180, 44
	v_readlane_b32 s45, v180, 45
	v_readlane_b32 s46, v180, 46
	v_readlane_b32 s47, v180, 47
	v_readlane_b32 s48, v180, 48
	v_readlane_b32 s49, v180, 49
	v_readlane_b32 s50, v180, 50
	v_readlane_b32 s51, v180, 51
	v_readlane_b32 s52, v180, 52
	v_readlane_b32 s53, v180, 53
	v_readlane_b32 s54, v180, 54
	v_readlane_b32 s55, v180, 55
	v_readlane_b32 s56, v180, 56
	v_readlane_b32 s57, v180, 57
	v_readlane_b32 s58, v180, 58
	v_readlane_b32 s59, v180, 59
	v_readlane_b32 s60, v180, 60
	v_readlane_b32 s61, v180, 61
	v_readlane_b32 s62, v180, 62
	v_readlane_b32 s63, v180, 63
	v_readlane_b32 s64, v181, 0
	v_readlane_b32 s65, v181, 1
	v_readlane_b32 s66, v181, 2
	v_readlane_b32 s67, v181, 3
	v_readlane_b32 s68, v181, 4
	v_readlane_b32 s69, v181, 5
	v_readlane_b32 s70, v181, 6
	v_readlane_b32 s71, v181, 7
	v_readlane_b32 s72, v181, 8
	v_readlane_b32 s73, v181, 9
	v_readlane_b32 s74, v181, 10
	v_readlane_b32 s75, v181, 11
	v_readlane_b32 s76, v181, 12
	v_readlane_b32 s77, v181, 13
	v_readlane_b32 s78, v181, 14
	v_readlane_b32 s79, v181, 15
	v_readlane_b32 s80, v181, 16
	v_readlane_b32 s81, v181, 17
	v_readlane_b32 s82, v181, 18
	v_readlane_b32 s83, v181, 19
	v_readlane_b32 s84, v181, 20
	v_readlane_b32 s85, v181, 21
	v_readlane_b32 s86, v181, 22
	v_readlane_b32 s87, v181, 23
	v_readlane_b32 s88, v181, 24
	v_readlane_b32 s89, v181, 25
	v_readlane_b32 s90, v181, 26
	v_readlane_b32 s91, v181, 27
	v_readlane_b32 s92, v181, 28
	v_readlane_b32 s93, v181, 29
	v_readlane_b32 s94, v181, 30
	v_readlane_b32 s95, v181, 31
	v_readlane_b32 s96, v181, 32
	v_readlane_b32 s97, v181, 33
	v_readlane_b32 s98, v181, 34
	v_readlane_b32 s99, v181, 35
	v_readlane_b32 s100, v181, 36
	v_readlane_b32 s101, v181, 37
	v_readlane_b32 vcc_lo, v181, 38
	v_readlane_b32 vcc_hi, v181, 39
